# v62 + prep tail rebalance: the 16 compress-bias tiles run on workgroups 128-143 (idle during the c1/c2 tiles) instead of 0-15
# speedup vs baseline: 1.0047x; 1.0017x over previous
; DI void phase_prep(const Params& P, unsigned char* smem, int L, int G) {
;     ...
;     for (int t = L; t < 16; t += G) {
;       const int which = t >> 3, n0 = (t & 7) * 32;
;       const int kp = tid >> 5, nn = tid & 31;
;       const float* W = which ? P.l2_phi_v1 : P.l2_phi_k1;
;       float s1 = 0.f;
;       for (int k = kp * 128; k < kp * 128 + 128; ++k) s1 += P.l2_cmp_pos[k] * W[(size_t)k * 256 + n0 + nn];
;       __syncthreads();
;       red[kp * 32 + nn] = s1;
;       __syncthreads();
;       if (tid < 32) { float a = 0.f; for (int q = 0; q < 16; ++q) a += red[q * 32 + tid]; bias[which * 256 + n0 + tid] = a; }
;     }
.LBB0_160:
	s_add_u32 s6, s72, 0x2b68000
	s_addc_u32 s7, s73, 0
	s_cmp_ge_u32 s74, 0x90
	s_cselect_b32 s99, 0x80, 0
	s_sub_i32 s98, s70, s99
	s_cmp_lt_u32 s98, 16
	s_cselect_b64 s[30:31], -1, 0
	s_andn2_b64 vcc, exec, s[30:31]
	s_barrier
	s_cbranch_vccnz .LBB0_167
	v_and_b32_e32 v4, 0xffffff80, v1
	v_mov_b32_e32 v2, s80
	v_mov_b32_e32 v3, s81
	v_ashrrev_i32_e32 v5, 31, v4
	v_and_b32_e32 v6, 31, v0
	v_add_u32_e32 v11, -1, v4
	v_lshl_add_u64 v[2:3], v[4:5], 2, v[2:3]
	v_lshlrev_b64 v[4:5], 10, v[4:5]
	v_cmp_gt_i32_e32 vcc, 32, v0
	v_or_b32_e32 v10, 0x7f, v1
	v_lshl_or_b32 v4, v6, 2, v4
	s_lshl_b32 s33, s98, 5
	s_lshl_b32 s34, s74, 5
	s_mov_b32 s3, 0
	s_mov_b64 s[4:5], 0x400
	v_add_u32_e32 v12, 0x400, v1
	s_mov_b32 s35, s98
	s_branch .LBB0_163
